# tail weight conversion: 16 per-k gain loads batched with counted waits (were 16 serialized round trips per item)
# speedup vs baseline: 1.0147x; 1.0147x over previous
; template <bool UPPERM> __device__ __forceinline__ void p0_transpose_item(const float* W, int K, int N, bf16_t* WT, const float* gk, LAS float* scr, int item, int lane) {
;     ...
;     for (int i = 0; i < 16; ++i) v[i] = *(const f32x4*)(W + (size_t)(k0 + 4 * i + r4) * N + n0 + c4);
;     if (gk) {
; #pragma unroll
;         for (int i = 0; i < 16; ++i) v[i] *= gk[k0 + 4 * i + r4];
.LBB0_382:
	s_ashr_i32 s35, s34, 31
	s_lshl_b64 s[36:37], s[34:35], 2
	s_add_u32 s36, s30, s36
	s_addc_u32 s37, s31, s37
	v_lshl_add_u64 v[58:59], s[36:37], 0, v[0:1]
	v_mul_hi_i32_i24_e32 v5, s20, v103
	v_mul_i32_i24_e32 v4, s20, v103
	v_mul_hi_i32_i24_e32 v11, s20, v102
	v_mul_i32_i24_e32 v10, s20, v102
	v_mul_hi_i32_i24_e32 v13, s20, v101
	v_mul_i32_i24_e32 v12, s20, v101
	v_mul_hi_i32_i24_e32 v19, s20, v100
	v_mul_i32_i24_e32 v18, s20, v100
	v_mul_hi_i32_i24_e32 v21, s20, v99
	v_mul_i32_i24_e32 v20, s20, v99
	v_mul_hi_i32_i24_e32 v27, s20, v98
	v_mul_i32_i24_e32 v26, s20, v98
	v_mul_hi_i32_i24_e32 v29, s20, v97
	v_mul_i32_i24_e32 v28, s20, v97
	v_mul_hi_i32_i24_e32 v35, s20, v96
	v_mul_i32_i24_e32 v34, s20, v96
	v_mul_hi_i32_i24_e32 v37, s20, v95
	v_mul_i32_i24_e32 v36, s20, v95
	v_mul_hi_i32_i24_e32 v43, s20, v94
	v_mul_i32_i24_e32 v42, s20, v94
	v_mul_hi_i32_i24_e32 v45, s20, v93
	v_mul_i32_i24_e32 v44, s20, v93
	v_mul_hi_i32_i24_e32 v51, s20, v92
	v_mul_i32_i24_e32 v50, s20, v92
	v_mul_hi_i32_i24_e32 v53, s20, v91
	v_mul_i32_i24_e32 v52, s20, v91
	v_mul_hi_i32_i24_e32 v61, s20, v90
	v_mul_i32_i24_e32 v60, s20, v90
	v_mul_hi_i32_i24_e32 v63, s20, v89
	v_mul_i32_i24_e32 v62, s20, v89
	v_lshl_add_u64 v[2:3], v[72:73], 2, v[58:59]
	v_lshl_add_u64 v[4:5], v[4:5], 2, v[58:59]
	v_lshl_add_u64 v[10:11], v[10:11], 2, v[58:59]
	v_lshl_add_u64 v[12:13], v[12:13], 2, v[58:59]
	v_lshl_add_u64 v[18:19], v[18:19], 2, v[58:59]
	v_lshl_add_u64 v[20:21], v[20:21], 2, v[58:59]
	v_lshl_add_u64 v[26:27], v[26:27], 2, v[58:59]
	v_lshl_add_u64 v[28:29], v[28:29], 2, v[58:59]
	v_lshl_add_u64 v[34:35], v[34:35], 2, v[58:59]
	v_lshl_add_u64 v[36:37], v[36:37], 2, v[58:59]
	v_lshl_add_u64 v[42:43], v[42:43], 2, v[58:59]
	v_lshl_add_u64 v[44:45], v[44:45], 2, v[58:59]
	v_lshl_add_u64 v[50:51], v[50:51], 2, v[58:59]
	v_lshl_add_u64 v[52:53], v[52:53], 2, v[58:59]
	v_lshl_add_u64 v[60:61], v[60:61], 2, v[58:59]
	v_lshl_add_u64 v[58:59], v[62:63], 2, v[58:59]
	global_load_dwordx4 v[6:9], v[2:3], off
	s_nop 0
	global_load_dwordx4 v[2:5], v[4:5], off
	s_nop 0
	global_load_dwordx4 v[14:17], v[10:11], off
	s_nop 0
	global_load_dwordx4 v[10:13], v[12:13], off
	s_nop 0
	global_load_dwordx4 v[22:25], v[18:19], off
	s_nop 0
	global_load_dwordx4 v[18:21], v[20:21], off
	s_nop 0
	global_load_dwordx4 v[30:33], v[26:27], off
	s_nop 0
	global_load_dwordx4 v[26:29], v[28:29], off
	s_nop 0
	global_load_dwordx4 v[38:41], v[34:35], off
	s_nop 0
	global_load_dwordx4 v[34:37], v[36:37], off
	s_nop 0
	global_load_dwordx4 v[46:49], v[42:43], off
	s_nop 0
	global_load_dwordx4 v[42:45], v[44:45], off
	s_nop 0
	global_load_dwordx4 v[54:57], v[50:51], off
	s_nop 0
	global_load_dwordx4 v[50:53], v[52:53], off
	s_nop 0
	global_load_dwordx4 v[62:65], v[60:61], off
	s_nop 0
	global_load_dwordx4 v[58:61], v[58:59], off
	s_cmp_eq_u64 s[18:19], 0
	s_cbranch_scc1 .LBB0_384
	v_ashrrev_i32_e32 v71, 31, v70
	v_lshl_add_u64 v[74:75], v[70:71], 2, s[18:19]
	global_load_dword v110, v[74:75], off
	global_load_dword v112, v[74:75], off offset:16
	global_load_dword v114, v[74:75], off offset:32
	global_load_dword v116, v[74:75], off offset:48
	global_load_dword v118, v[74:75], off offset:64
	global_load_dword v120, v[74:75], off offset:80
	global_load_dword v122, v[74:75], off offset:96
	global_load_dword v124, v[74:75], off offset:112
	global_load_dword v126, v[74:75], off offset:128
	global_load_dword v128, v[74:75], off offset:144
	global_load_dword v130, v[74:75], off offset:160
	global_load_dword v132, v[74:75], off offset:176
	global_load_dword v134, v[74:75], off offset:192
	global_load_dword v136, v[74:75], off offset:208
	global_load_dword v138, v[74:75], off offset:224
	global_load_dword v140, v[74:75], off offset:240
	s_waitcnt vmcnt(15)
	v_pk_mul_f32 v[8:9], v[8:9], v[110:111] op_sel_hi:[1,0]
	v_pk_mul_f32 v[6:7], v[6:7], v[110:111] op_sel_hi:[1,0]
	s_waitcnt vmcnt(14)
	v_pk_mul_f32 v[4:5], v[4:5], v[112:113] op_sel_hi:[1,0]
	v_pk_mul_f32 v[2:3], v[2:3], v[112:113] op_sel_hi:[1,0]
	s_waitcnt vmcnt(13)
	v_pk_mul_f32 v[16:17], v[16:17], v[114:115] op_sel_hi:[1,0]
	v_pk_mul_f32 v[14:15], v[14:15], v[114:115] op_sel_hi:[1,0]
	s_waitcnt vmcnt(12)
	v_pk_mul_f32 v[12:13], v[12:13], v[116:117] op_sel_hi:[1,0]
	v_pk_mul_f32 v[10:11], v[10:11], v[116:117] op_sel_hi:[1,0]
	s_waitcnt vmcnt(11)
	v_pk_mul_f32 v[24:25], v[24:25], v[118:119] op_sel_hi:[1,0]
	v_pk_mul_f32 v[22:23], v[22:23], v[118:119] op_sel_hi:[1,0]
	s_waitcnt vmcnt(10)
	v_pk_mul_f32 v[20:21], v[20:21], v[120:121] op_sel_hi:[1,0]
	v_pk_mul_f32 v[18:19], v[18:19], v[120:121] op_sel_hi:[1,0]
	s_waitcnt vmcnt(9)
	v_pk_mul_f32 v[32:33], v[32:33], v[122:123] op_sel_hi:[1,0]
	v_pk_mul_f32 v[30:31], v[30:31], v[122:123] op_sel_hi:[1,0]
	s_waitcnt vmcnt(8)
	v_pk_mul_f32 v[28:29], v[28:29], v[124:125] op_sel_hi:[1,0]
	v_pk_mul_f32 v[26:27], v[26:27], v[124:125] op_sel_hi:[1,0]
	s_waitcnt vmcnt(7)
	v_pk_mul_f32 v[40:41], v[40:41], v[126:127] op_sel_hi:[1,0]
	v_pk_mul_f32 v[38:39], v[38:39], v[126:127] op_sel_hi:[1,0]
	s_waitcnt vmcnt(6)
	v_pk_mul_f32 v[36:37], v[36:37], v[128:129] op_sel_hi:[1,0]
	v_pk_mul_f32 v[34:35], v[34:35], v[128:129] op_sel_hi:[1,0]
	s_waitcnt vmcnt(5)
	v_pk_mul_f32 v[48:49], v[48:49], v[130:131] op_sel_hi:[1,0]
	v_pk_mul_f32 v[46:47], v[46:47], v[130:131] op_sel_hi:[1,0]
	s_waitcnt vmcnt(4)
	v_pk_mul_f32 v[44:45], v[44:45], v[132:133] op_sel_hi:[1,0]
	v_pk_mul_f32 v[42:43], v[42:43], v[132:133] op_sel_hi:[1,0]
	s_waitcnt vmcnt(3)
	v_pk_mul_f32 v[56:57], v[56:57], v[134:135] op_sel_hi:[1,0]
	v_pk_mul_f32 v[54:55], v[54:55], v[134:135] op_sel_hi:[1,0]
	s_waitcnt vmcnt(2)
	v_pk_mul_f32 v[52:53], v[52:53], v[136:137] op_sel_hi:[1,0]
	v_pk_mul_f32 v[50:51], v[50:51], v[136:137] op_sel_hi:[1,0]
	s_waitcnt vmcnt(1)
	v_pk_mul_f32 v[64:65], v[64:65], v[138:139] op_sel_hi:[1,0]
	v_pk_mul_f32 v[62:63], v[62:63], v[138:139] op_sel_hi:[1,0]
	s_waitcnt vmcnt(0)
	v_pk_mul_f32 v[60:61], v[60:61], v[140:141] op_sel_hi:[1,0]
	v_pk_mul_f32 v[58:59], v[58:59], v[140:141] op_sel_hi:[1,0]

; template <bool UPPERM> __device__ __forceinline__ void p0_transpose_item(const float* W, int K, int N, bf16_t* WT, const float* gk, LAS float* scr, int item, int lane) {
;     ...
;     for (int i = 0; i < 16; ++i) v[i] = *(const f32x4*)(W + (size_t)(k0 + 4 * i + r4) * N + n0 + c4);
;     if (gk) {
; #pragma unroll
;         for (int i = 0; i < 16; ++i) v[i] *= gk[k0 + 4 * i + r4];
.LBB0_385:
	s_ashr_i32 s35, s34, 31
	s_lshl_b64 s[34:35], s[34:35], 2
	s_add_u32 s30, s30, s34
	s_addc_u32 s31, s31, s35
	v_lshl_add_u64 v[58:59], s[30:31], 0, v[0:1]
	v_mul_hi_i32_i24_e32 v5, s20, v103
	v_mul_i32_i24_e32 v4, s20, v103
	v_mul_hi_i32_i24_e32 v11, s20, v102
	v_mul_i32_i24_e32 v10, s20, v102
	v_mul_hi_i32_i24_e32 v13, s20, v101
	v_mul_i32_i24_e32 v12, s20, v101
	v_mul_hi_i32_i24_e32 v19, s20, v100
	v_mul_i32_i24_e32 v18, s20, v100
	v_mul_hi_i32_i24_e32 v21, s20, v99
	v_mul_i32_i24_e32 v20, s20, v99
	v_mul_hi_i32_i24_e32 v27, s20, v98
	v_mul_i32_i24_e32 v26, s20, v98
	v_mul_hi_i32_i24_e32 v29, s20, v97
	v_mul_i32_i24_e32 v28, s20, v97
	v_mul_hi_i32_i24_e32 v35, s20, v96
	v_mul_i32_i24_e32 v34, s20, v96
	v_mul_hi_i32_i24_e32 v37, s20, v95
	v_mul_i32_i24_e32 v36, s20, v95
	v_mul_hi_i32_i24_e32 v43, s20, v94
	v_mul_i32_i24_e32 v42, s20, v94
	v_mul_hi_i32_i24_e32 v45, s20, v93
	v_mul_i32_i24_e32 v44, s20, v93
	v_mul_hi_i32_i24_e32 v51, s20, v92
	v_mul_i32_i24_e32 v50, s20, v92
	v_mul_hi_i32_i24_e32 v53, s20, v91
	v_mul_i32_i24_e32 v52, s20, v91
	v_mul_hi_i32_i24_e32 v61, s20, v90
	v_mul_i32_i24_e32 v60, s20, v90
	v_mul_hi_i32_i24_e32 v63, s20, v89
	v_mul_i32_i24_e32 v62, s20, v89
	v_lshl_add_u64 v[2:3], v[72:73], 2, v[58:59]
	v_lshl_add_u64 v[4:5], v[4:5], 2, v[58:59]
	v_lshl_add_u64 v[10:11], v[10:11], 2, v[58:59]
	v_lshl_add_u64 v[12:13], v[12:13], 2, v[58:59]
	v_lshl_add_u64 v[18:19], v[18:19], 2, v[58:59]
	v_lshl_add_u64 v[20:21], v[20:21], 2, v[58:59]
	v_lshl_add_u64 v[26:27], v[26:27], 2, v[58:59]
	v_lshl_add_u64 v[28:29], v[28:29], 2, v[58:59]
	v_lshl_add_u64 v[34:35], v[34:35], 2, v[58:59]
	v_lshl_add_u64 v[36:37], v[36:37], 2, v[58:59]
	v_lshl_add_u64 v[42:43], v[42:43], 2, v[58:59]
	v_lshl_add_u64 v[44:45], v[44:45], 2, v[58:59]
	v_lshl_add_u64 v[50:51], v[50:51], 2, v[58:59]
	v_lshl_add_u64 v[52:53], v[52:53], 2, v[58:59]
	v_lshl_add_u64 v[60:61], v[60:61], 2, v[58:59]
	v_lshl_add_u64 v[58:59], v[62:63], 2, v[58:59]
	global_load_dwordx4 v[6:9], v[2:3], off
	s_nop 0
	global_load_dwordx4 v[2:5], v[4:5], off
	s_nop 0
	global_load_dwordx4 v[14:17], v[10:11], off
	s_nop 0
	global_load_dwordx4 v[10:13], v[12:13], off
	s_nop 0
	global_load_dwordx4 v[22:25], v[18:19], off
	s_nop 0
	global_load_dwordx4 v[18:21], v[20:21], off
	s_nop 0
	global_load_dwordx4 v[30:33], v[26:27], off
	s_nop 0
	global_load_dwordx4 v[26:29], v[28:29], off
	s_nop 0
	global_load_dwordx4 v[38:41], v[34:35], off
	s_nop 0
	global_load_dwordx4 v[34:37], v[36:37], off
	s_nop 0
	global_load_dwordx4 v[46:49], v[42:43], off
	s_nop 0
	global_load_dwordx4 v[42:45], v[44:45], off
	s_nop 0
	global_load_dwordx4 v[54:57], v[50:51], off
	s_nop 0
	global_load_dwordx4 v[50:53], v[52:53], off
	s_nop 0
	global_load_dwordx4 v[62:65], v[60:61], off
	s_nop 0
	global_load_dwordx4 v[58:61], v[58:59], off
	s_cmp_eq_u64 s[18:19], 0
	s_cbranch_scc1 .LBB0_361
	v_ashrrev_i32_e32 v71, 31, v70
	v_lshl_add_u64 v[70:71], v[70:71], 2, s[18:19]
	global_load_dword v110, v[70:71], off
	global_load_dword v112, v[70:71], off offset:16
	global_load_dword v114, v[70:71], off offset:32
	global_load_dword v116, v[70:71], off offset:48
	global_load_dword v118, v[70:71], off offset:64
	global_load_dword v120, v[70:71], off offset:80
	global_load_dword v122, v[70:71], off offset:96
	global_load_dword v124, v[70:71], off offset:112
	global_load_dword v126, v[70:71], off offset:128
	global_load_dword v128, v[70:71], off offset:144
	global_load_dword v130, v[70:71], off offset:160
	global_load_dword v132, v[70:71], off offset:176
	global_load_dword v134, v[70:71], off offset:192
	global_load_dword v136, v[70:71], off offset:208
	global_load_dword v138, v[70:71], off offset:224
	global_load_dword v140, v[70:71], off offset:240
	s_waitcnt vmcnt(15)
	v_pk_mul_f32 v[8:9], v[8:9], v[110:111] op_sel_hi:[1,0]
	v_pk_mul_f32 v[6:7], v[6:7], v[110:111] op_sel_hi:[1,0]
	s_waitcnt vmcnt(14)
	v_pk_mul_f32 v[4:5], v[4:5], v[112:113] op_sel_hi:[1,0]
	v_pk_mul_f32 v[2:3], v[2:3], v[112:113] op_sel_hi:[1,0]
	s_waitcnt vmcnt(13)
	v_pk_mul_f32 v[16:17], v[16:17], v[114:115] op_sel_hi:[1,0]
	v_pk_mul_f32 v[14:15], v[14:15], v[114:115] op_sel_hi:[1,0]
	s_waitcnt vmcnt(12)
	v_pk_mul_f32 v[12:13], v[12:13], v[116:117] op_sel_hi:[1,0]
	v_pk_mul_f32 v[10:11], v[10:11], v[116:117] op_sel_hi:[1,0]
	s_waitcnt vmcnt(11)
	v_pk_mul_f32 v[24:25], v[24:25], v[118:119] op_sel_hi:[1,0]
	v_pk_mul_f32 v[22:23], v[22:23], v[118:119] op_sel_hi:[1,0]
	s_waitcnt vmcnt(10)
	v_pk_mul_f32 v[20:21], v[20:21], v[120:121] op_sel_hi:[1,0]
	v_pk_mul_f32 v[18:19], v[18:19], v[120:121] op_sel_hi:[1,0]
	s_waitcnt vmcnt(9)
	v_pk_mul_f32 v[32:33], v[32:33], v[122:123] op_sel_hi:[1,0]
	v_pk_mul_f32 v[30:31], v[30:31], v[122:123] op_sel_hi:[1,0]
	s_waitcnt vmcnt(8)
	v_pk_mul_f32 v[28:29], v[28:29], v[124:125] op_sel_hi:[1,0]
	v_pk_mul_f32 v[26:27], v[26:27], v[124:125] op_sel_hi:[1,0]
	s_waitcnt vmcnt(7)
	v_pk_mul_f32 v[40:41], v[40:41], v[126:127] op_sel_hi:[1,0]
	v_pk_mul_f32 v[38:39], v[38:39], v[126:127] op_sel_hi:[1,0]
	s_waitcnt vmcnt(6)
	v_pk_mul_f32 v[36:37], v[36:37], v[128:129] op_sel_hi:[1,0]
	v_pk_mul_f32 v[34:35], v[34:35], v[128:129] op_sel_hi:[1,0]
	s_waitcnt vmcnt(5)
	v_pk_mul_f32 v[48:49], v[48:49], v[130:131] op_sel_hi:[1,0]
	v_pk_mul_f32 v[46:47], v[46:47], v[130:131] op_sel_hi:[1,0]
	s_waitcnt vmcnt(4)
	v_pk_mul_f32 v[44:45], v[44:45], v[132:133] op_sel_hi:[1,0]
	v_pk_mul_f32 v[42:43], v[42:43], v[132:133] op_sel_hi:[1,0]
	s_waitcnt vmcnt(3)
	v_pk_mul_f32 v[56:57], v[56:57], v[134:135] op_sel_hi:[1,0]
	v_pk_mul_f32 v[54:55], v[54:55], v[134:135] op_sel_hi:[1,0]
	s_waitcnt vmcnt(2)
	v_pk_mul_f32 v[52:53], v[52:53], v[136:137] op_sel_hi:[1,0]
	v_pk_mul_f32 v[50:51], v[50:51], v[136:137] op_sel_hi:[1,0]
	s_waitcnt vmcnt(1)
	v_pk_mul_f32 v[64:65], v[64:65], v[138:139] op_sel_hi:[1,0]
	v_pk_mul_f32 v[62:63], v[62:63], v[138:139] op_sel_hi:[1,0]
	s_waitcnt vmcnt(0)
	v_pk_mul_f32 v[60:61], v[60:61], v[140:141] op_sel_hi:[1,0]
	v_pk_mul_f32 v[58:59], v[58:59], v[140:141] op_sel_hi:[1,0]
	s_branch .LBB0_361

; template <bool UPPERM> __device__ __forceinline__ void p0_transpose_item(const float* W, int K, int N, bf16_t* WT, const float* gk, LAS float* scr, int item, int lane) {
;     const int nblk = N / 64, kb = item / nblk, nb = item % nblk, k0 = 64 * kb, n0 = 64 * nb;
;     const int dn0 = !UPPERM ? n0 : (n0 < FF ? ((n0 >> 7) * 256 + 2 * (n0 & 127)) : ((((n0 - FF) >> 7) * 256) + 2 * ((n0 - FF) & 127) + 32));
;     const int r4 = lane >> 4, c4 = (lane & 15) * 4;
;     f32x4 v[16];
; #pragma unroll
;     for (int i = 0; i < 16; ++i) v[i] = *(const f32x4*)(W + (size_t)(k0 + 4 * i + r4) * N + n0 + c4);
.LBB0_813:
	s_lshr_b32 s36, s44, 6
	v_cvt_f32_i32_e32 v0, s36
	s_sext_i32_i16 s16, s45
	v_cvt_f32_i32_e32 v2, s16
	s_ashr_i32 s16, s16, 30
	v_rcp_iflag_f32_e32 v3, v0
	s_or_b32 s37, s16, 1
	s_mov_b64 s[40:41], -1
	v_mul_f32_e32 v3, v2, v3
	v_trunc_f32_e32 v3, v3
	v_fma_f32 v2, -v3, v0, v2
	v_cvt_i32_f32_e32 v3, v3
	v_cmp_ge_f32_e64 s[16:17], |v2|, v0
	s_and_b64 s[16:17], s[16:17], exec
	s_cselect_b32 s16, s37, 0
	v_readfirstlane_b32 s17, v3
	s_add_i32 s16, s17, s16
	s_sext_i32_i16 s17, s16
	s_mul_i32 s16, s16, s36
	s_sub_i32 s16, s45, s16
	s_sext_i32_i16 s43, s16
	s_lshl_b32 s16, s17, 6
	v_or_b32_e32 v70, s16, v67
	s_lshl_b32 s36, s43, 6
	s_andn2_b64 vcc, exec, s[38:39]
	v_lshlrev_b32_e32 v0, 2, v66
	v_mul_hi_i32_i24_e32 v73, s44, v70
	v_mul_i32_i24_e32 v72, s44, v70
	v_or_b32_e32 v103, 4, v70
	v_or_b32_e32 v102, 8, v70
	v_or_b32_e32 v101, 12, v70
	v_or_b32_e32 v100, 16, v70
	v_or_b32_e32 v99, 20, v70
	v_or_b32_e32 v98, 24, v70
	v_or_b32_e32 v97, 28, v70
	v_or_b32_e32 v96, 32, v70
	v_or_b32_e32 v95, 36, v70
	v_or_b32_e32 v94, 40, v70
	v_or_b32_e32 v93, 44, v70
	v_or_b32_e32 v92, 48, v70
	v_or_b32_e32 v91, 52, v70
	v_or_b32_e32 v90, 56, v70
	v_or_b32_e32 v89, 60, v70
	s_cbranch_vccz .LBB0_817
	s_ashr_i32 s37, s36, 31
	s_lshl_b64 s[38:39], s[36:37], 2
	s_add_u32 s38, s34, s38
	s_addc_u32 s39, s35, s39
	v_lshl_add_u64 v[58:59], s[38:39], 0, v[0:1]
	v_mul_hi_i32_i24_e32 v5, s44, v103
	v_mul_i32_i24_e32 v4, s44, v103
	v_mul_hi_i32_i24_e32 v11, s44, v102
	v_mul_i32_i24_e32 v10, s44, v102
	v_mul_hi_i32_i24_e32 v13, s44, v101
	v_mul_i32_i24_e32 v12, s44, v101
	v_mul_hi_i32_i24_e32 v19, s44, v100
	v_mul_i32_i24_e32 v18, s44, v100
	v_mul_hi_i32_i24_e32 v21, s44, v99
	v_mul_i32_i24_e32 v20, s44, v99
	v_mul_hi_i32_i24_e32 v27, s44, v98
	v_mul_i32_i24_e32 v26, s44, v98
	v_mul_hi_i32_i24_e32 v29, s44, v97
	v_mul_i32_i24_e32 v28, s44, v97
	v_mul_hi_i32_i24_e32 v35, s44, v96
	v_mul_i32_i24_e32 v34, s44, v96
	v_mul_hi_i32_i24_e32 v37, s44, v95
	v_mul_i32_i24_e32 v36, s44, v95
	v_mul_hi_i32_i24_e32 v43, s44, v94
	v_mul_i32_i24_e32 v42, s44, v94
	v_mul_hi_i32_i24_e32 v45, s44, v93
	v_mul_i32_i24_e32 v44, s44, v93
	v_mul_hi_i32_i24_e32 v51, s44, v92
	v_mul_i32_i24_e32 v50, s44, v92
	v_mul_hi_i32_i24_e32 v53, s44, v91
	v_mul_i32_i24_e32 v52, s44, v91
	v_mul_hi_i32_i24_e32 v61, s44, v90
	v_mul_i32_i24_e32 v60, s44, v90
	v_mul_hi_i32_i24_e32 v63, s44, v89
	v_mul_i32_i24_e32 v62, s44, v89
	v_lshl_add_u64 v[2:3], v[72:73], 2, v[58:59]
	v_lshl_add_u64 v[4:5], v[4:5], 2, v[58:59]
	v_lshl_add_u64 v[10:11], v[10:11], 2, v[58:59]
	v_lshl_add_u64 v[12:13], v[12:13], 2, v[58:59]
	v_lshl_add_u64 v[18:19], v[18:19], 2, v[58:59]
	v_lshl_add_u64 v[20:21], v[20:21], 2, v[58:59]
	v_lshl_add_u64 v[26:27], v[26:27], 2, v[58:59]
	v_lshl_add_u64 v[28:29], v[28:29], 2, v[58:59]
	v_lshl_add_u64 v[34:35], v[34:35], 2, v[58:59]
	v_lshl_add_u64 v[36:37], v[36:37], 2, v[58:59]
	v_lshl_add_u64 v[42:43], v[42:43], 2, v[58:59]
	v_lshl_add_u64 v[44:45], v[44:45], 2, v[58:59]
	v_lshl_add_u64 v[50:51], v[50:51], 2, v[58:59]
	v_lshl_add_u64 v[52:53], v[52:53], 2, v[58:59]
	v_lshl_add_u64 v[60:61], v[60:61], 2, v[58:59]
	v_lshl_add_u64 v[58:59], v[62:63], 2, v[58:59]
	global_load_dwordx4 v[6:9], v[2:3], off
	s_nop 0
	global_load_dwordx4 v[2:5], v[4:5], off
	s_nop 0
	global_load_dwordx4 v[14:17], v[10:11], off
	s_nop 0
	global_load_dwordx4 v[10:13], v[12:13], off
	s_nop 0
	global_load_dwordx4 v[22:25], v[18:19], off
	s_nop 0
	global_load_dwordx4 v[18:21], v[20:21], off
	s_nop 0
	global_load_dwordx4 v[30:33], v[26:27], off
	s_nop 0
	global_load_dwordx4 v[26:29], v[28:29], off
	s_nop 0
	global_load_dwordx4 v[38:41], v[34:35], off
	s_nop 0
	global_load_dwordx4 v[34:37], v[36:37], off
	s_nop 0
	global_load_dwordx4 v[46:49], v[42:43], off
	s_nop 0
	global_load_dwordx4 v[42:45], v[44:45], off
	s_nop 0
	global_load_dwordx4 v[54:57], v[50:51], off
	s_nop 0
	global_load_dwordx4 v[50:53], v[52:53], off
	s_nop 0
	global_load_dwordx4 v[62:65], v[60:61], off
	s_nop 0
	global_load_dwordx4 v[58:61], v[58:59], off
	s_cmp_eq_u64 s[30:31], 0
	s_cbranch_scc1 .LBB0_816
; template <bool UPPERM> __device__ __forceinline__ void p0_transpose_item(const float* W, int K, int N, bf16_t* WT, const float* gk, LAS float* scr, int item, int lane) {
;     ...
;     for (int i = 0; i < 16; ++i) v[i] = *(const f32x4*)(W + (size_t)(k0 + 4 * i + r4) * N + n0 + c4);
;     if (gk) {
; #pragma unroll
;         for (int i = 0; i < 16; ++i) v[i] *= gk[k0 + 4 * i + r4];
	v_ashrrev_i32_e32 v71, 31, v70
	v_lshl_add_u64 v[74:75], v[70:71], 2, s[30:31]
	global_load_dword v110, v[74:75], off
	global_load_dword v112, v[74:75], off offset:16
	global_load_dword v114, v[74:75], off offset:32
	global_load_dword v116, v[74:75], off offset:48
	global_load_dword v118, v[74:75], off offset:64
	global_load_dword v120, v[74:75], off offset:80
	global_load_dword v122, v[74:75], off offset:96
	global_load_dword v124, v[74:75], off offset:112
	global_load_dword v126, v[74:75], off offset:128
	global_load_dword v128, v[74:75], off offset:144
	global_load_dword v130, v[74:75], off offset:160
	global_load_dword v132, v[74:75], off offset:176
	global_load_dword v134, v[74:75], off offset:192
	global_load_dword v136, v[74:75], off offset:208
	global_load_dword v138, v[74:75], off offset:224
	global_load_dword v140, v[74:75], off offset:240
	s_waitcnt vmcnt(15)
	v_pk_mul_f32 v[8:9], v[8:9], v[110:111] op_sel_hi:[1,0]
	v_pk_mul_f32 v[6:7], v[6:7], v[110:111] op_sel_hi:[1,0]
	s_waitcnt vmcnt(14)
	v_pk_mul_f32 v[4:5], v[4:5], v[112:113] op_sel_hi:[1,0]
	v_pk_mul_f32 v[2:3], v[2:3], v[112:113] op_sel_hi:[1,0]
	s_waitcnt vmcnt(13)
	v_pk_mul_f32 v[16:17], v[16:17], v[114:115] op_sel_hi:[1,0]
	v_pk_mul_f32 v[14:15], v[14:15], v[114:115] op_sel_hi:[1,0]
	s_waitcnt vmcnt(12)
	v_pk_mul_f32 v[12:13], v[12:13], v[116:117] op_sel_hi:[1,0]
	v_pk_mul_f32 v[10:11], v[10:11], v[116:117] op_sel_hi:[1,0]
	s_waitcnt vmcnt(11)
	v_pk_mul_f32 v[24:25], v[24:25], v[118:119] op_sel_hi:[1,0]
	v_pk_mul_f32 v[22:23], v[22:23], v[118:119] op_sel_hi:[1,0]
	s_waitcnt vmcnt(10)
	v_pk_mul_f32 v[20:21], v[20:21], v[120:121] op_sel_hi:[1,0]
	v_pk_mul_f32 v[18:19], v[18:19], v[120:121] op_sel_hi:[1,0]
	s_waitcnt vmcnt(9)
	v_pk_mul_f32 v[32:33], v[32:33], v[122:123] op_sel_hi:[1,0]
	v_pk_mul_f32 v[30:31], v[30:31], v[122:123] op_sel_hi:[1,0]
	s_waitcnt vmcnt(8)
	v_pk_mul_f32 v[28:29], v[28:29], v[124:125] op_sel_hi:[1,0]
	v_pk_mul_f32 v[26:27], v[26:27], v[124:125] op_sel_hi:[1,0]
	s_waitcnt vmcnt(7)
	v_pk_mul_f32 v[40:41], v[40:41], v[126:127] op_sel_hi:[1,0]
	v_pk_mul_f32 v[38:39], v[38:39], v[126:127] op_sel_hi:[1,0]
	s_waitcnt vmcnt(6)
	v_pk_mul_f32 v[36:37], v[36:37], v[128:129] op_sel_hi:[1,0]
	v_pk_mul_f32 v[34:35], v[34:35], v[128:129] op_sel_hi:[1,0]
	s_waitcnt vmcnt(5)
	v_pk_mul_f32 v[48:49], v[48:49], v[130:131] op_sel_hi:[1,0]
	v_pk_mul_f32 v[46:47], v[46:47], v[130:131] op_sel_hi:[1,0]
	s_waitcnt vmcnt(4)
	v_pk_mul_f32 v[44:45], v[44:45], v[132:133] op_sel_hi:[1,0]
	v_pk_mul_f32 v[42:43], v[42:43], v[132:133] op_sel_hi:[1,0]
	s_waitcnt vmcnt(3)
	v_pk_mul_f32 v[56:57], v[56:57], v[134:135] op_sel_hi:[1,0]
	v_pk_mul_f32 v[54:55], v[54:55], v[134:135] op_sel_hi:[1,0]
	s_waitcnt vmcnt(2)
	v_pk_mul_f32 v[52:53], v[52:53], v[136:137] op_sel_hi:[1,0]
	v_pk_mul_f32 v[50:51], v[50:51], v[136:137] op_sel_hi:[1,0]
	s_waitcnt vmcnt(1)
	v_pk_mul_f32 v[64:65], v[64:65], v[138:139] op_sel_hi:[1,0]
	v_pk_mul_f32 v[62:63], v[62:63], v[138:139] op_sel_hi:[1,0]
	s_waitcnt vmcnt(0)
	v_pk_mul_f32 v[60:61], v[60:61], v[140:141] op_sel_hi:[1,0]
	v_pk_mul_f32 v[58:59], v[58:59], v[140:141] op_sel_hi:[1,0]

; template <bool UPPERM> __device__ __forceinline__ void p0_transpose_item(const float* W, int K, int N, bf16_t* WT, const float* gk, LAS float* scr, int item, int lane) {
;     ...
;     for (int i = 0; i < 16; ++i) v[i] = *(const f32x4*)(W + (size_t)(k0 + 4 * i + r4) * N + n0 + c4);
;     if (gk) {
; #pragma unroll
;         for (int i = 0; i < 16; ++i) v[i] *= gk[k0 + 4 * i + r4];
.LBB0_817:
	s_and_b64 vcc, exec, s[40:41]
	s_cbranch_vccz .LBB0_795
	s_ashr_i32 s37, s36, 31
	s_lshl_b64 s[36:37], s[36:37], 2
	s_add_u32 s34, s34, s36
	s_addc_u32 s35, s35, s37
	v_lshl_add_u64 v[58:59], s[34:35], 0, v[0:1]
	v_mul_hi_i32_i24_e32 v5, s44, v103
	v_mul_i32_i24_e32 v4, s44, v103
	v_mul_hi_i32_i24_e32 v11, s44, v102
	v_mul_i32_i24_e32 v10, s44, v102
	v_mul_hi_i32_i24_e32 v13, s44, v101
	v_mul_i32_i24_e32 v12, s44, v101
	v_mul_hi_i32_i24_e32 v19, s44, v100
	v_mul_i32_i24_e32 v18, s44, v100
	v_mul_hi_i32_i24_e32 v21, s44, v99
	v_mul_i32_i24_e32 v20, s44, v99
	v_mul_hi_i32_i24_e32 v27, s44, v98
	v_mul_i32_i24_e32 v26, s44, v98
	v_mul_hi_i32_i24_e32 v29, s44, v97
	v_mul_i32_i24_e32 v28, s44, v97
	v_mul_hi_i32_i24_e32 v35, s44, v96
	v_mul_i32_i24_e32 v34, s44, v96
	v_mul_hi_i32_i24_e32 v37, s44, v95
	v_mul_i32_i24_e32 v36, s44, v95
	v_mul_hi_i32_i24_e32 v43, s44, v94
	v_mul_i32_i24_e32 v42, s44, v94
	v_mul_hi_i32_i24_e32 v45, s44, v93
	v_mul_i32_i24_e32 v44, s44, v93
	v_mul_hi_i32_i24_e32 v51, s44, v92
	v_mul_i32_i24_e32 v50, s44, v92
	v_mul_hi_i32_i24_e32 v53, s44, v91
	v_mul_i32_i24_e32 v52, s44, v91
	v_mul_hi_i32_i24_e32 v61, s44, v90
	v_mul_i32_i24_e32 v60, s44, v90
	v_mul_hi_i32_i24_e32 v63, s44, v89
	v_mul_i32_i24_e32 v62, s44, v89
	v_lshl_add_u64 v[2:3], v[72:73], 2, v[58:59]
	v_lshl_add_u64 v[4:5], v[4:5], 2, v[58:59]
	v_lshl_add_u64 v[10:11], v[10:11], 2, v[58:59]
	v_lshl_add_u64 v[12:13], v[12:13], 2, v[58:59]
	v_lshl_add_u64 v[18:19], v[18:19], 2, v[58:59]
	v_lshl_add_u64 v[20:21], v[20:21], 2, v[58:59]
	v_lshl_add_u64 v[26:27], v[26:27], 2, v[58:59]
	v_lshl_add_u64 v[28:29], v[28:29], 2, v[58:59]
	v_lshl_add_u64 v[34:35], v[34:35], 2, v[58:59]
	v_lshl_add_u64 v[36:37], v[36:37], 2, v[58:59]
	v_lshl_add_u64 v[42:43], v[42:43], 2, v[58:59]
	v_lshl_add_u64 v[44:45], v[44:45], 2, v[58:59]
	v_lshl_add_u64 v[50:51], v[50:51], 2, v[58:59]
	v_lshl_add_u64 v[52:53], v[52:53], 2, v[58:59]
	v_lshl_add_u64 v[60:61], v[60:61], 2, v[58:59]
	v_lshl_add_u64 v[58:59], v[62:63], 2, v[58:59]
	global_load_dwordx4 v[6:9], v[2:3], off
	s_nop 0
	global_load_dwordx4 v[2:5], v[4:5], off
	s_nop 0
	global_load_dwordx4 v[14:17], v[10:11], off
	s_nop 0
	global_load_dwordx4 v[10:13], v[12:13], off
	s_nop 0
	global_load_dwordx4 v[22:25], v[18:19], off
	s_nop 0
	global_load_dwordx4 v[18:21], v[20:21], off
	s_nop 0
	global_load_dwordx4 v[30:33], v[26:27], off
	s_nop 0
	global_load_dwordx4 v[26:29], v[28:29], off
	s_nop 0
	global_load_dwordx4 v[38:41], v[34:35], off
	s_nop 0
	global_load_dwordx4 v[34:37], v[36:37], off
	s_nop 0
	global_load_dwordx4 v[46:49], v[42:43], off
	s_nop 0
	global_load_dwordx4 v[42:45], v[44:45], off
	s_nop 0
	global_load_dwordx4 v[54:57], v[50:51], off
	s_nop 0
	global_load_dwordx4 v[50:53], v[52:53], off
	s_nop 0
	global_load_dwordx4 v[62:65], v[60:61], off
	s_nop 0
	global_load_dwordx4 v[58:61], v[58:59], off
	s_cmp_eq_u64 s[30:31], 0
	s_cbranch_scc1 .LBB0_794
	v_ashrrev_i32_e32 v71, 31, v70
	v_lshl_add_u64 v[70:71], v[70:71], 2, s[30:31]
	global_load_dword v110, v[70:71], off
	global_load_dword v112, v[70:71], off offset:16
	global_load_dword v114, v[70:71], off offset:32
	global_load_dword v116, v[70:71], off offset:48
	global_load_dword v118, v[70:71], off offset:64
	global_load_dword v120, v[70:71], off offset:80
	global_load_dword v122, v[70:71], off offset:96
	global_load_dword v124, v[70:71], off offset:112
	global_load_dword v126, v[70:71], off offset:128
	global_load_dword v128, v[70:71], off offset:144
	global_load_dword v130, v[70:71], off offset:160
	global_load_dword v132, v[70:71], off offset:176
	global_load_dword v134, v[70:71], off offset:192
	global_load_dword v136, v[70:71], off offset:208
	global_load_dword v138, v[70:71], off offset:224
	global_load_dword v140, v[70:71], off offset:240
	s_waitcnt vmcnt(15)
	v_pk_mul_f32 v[8:9], v[8:9], v[110:111] op_sel_hi:[1,0]
	v_pk_mul_f32 v[6:7], v[6:7], v[110:111] op_sel_hi:[1,0]
	s_waitcnt vmcnt(14)
	v_pk_mul_f32 v[4:5], v[4:5], v[112:113] op_sel_hi:[1,0]
	v_pk_mul_f32 v[2:3], v[2:3], v[112:113] op_sel_hi:[1,0]
	s_waitcnt vmcnt(13)
	v_pk_mul_f32 v[16:17], v[16:17], v[114:115] op_sel_hi:[1,0]
	v_pk_mul_f32 v[14:15], v[14:15], v[114:115] op_sel_hi:[1,0]
	s_waitcnt vmcnt(12)
	v_pk_mul_f32 v[12:13], v[12:13], v[116:117] op_sel_hi:[1,0]
	v_pk_mul_f32 v[10:11], v[10:11], v[116:117] op_sel_hi:[1,0]
	s_waitcnt vmcnt(11)
	v_pk_mul_f32 v[24:25], v[24:25], v[118:119] op_sel_hi:[1,0]
	v_pk_mul_f32 v[22:23], v[22:23], v[118:119] op_sel_hi:[1,0]
	s_waitcnt vmcnt(10)
	v_pk_mul_f32 v[20:21], v[20:21], v[120:121] op_sel_hi:[1,0]
	v_pk_mul_f32 v[18:19], v[18:19], v[120:121] op_sel_hi:[1,0]
	s_waitcnt vmcnt(9)
	v_pk_mul_f32 v[32:33], v[32:33], v[122:123] op_sel_hi:[1,0]
	v_pk_mul_f32 v[30:31], v[30:31], v[122:123] op_sel_hi:[1,0]
	s_waitcnt vmcnt(8)
	v_pk_mul_f32 v[28:29], v[28:29], v[124:125] op_sel_hi:[1,0]
	v_pk_mul_f32 v[26:27], v[26:27], v[124:125] op_sel_hi:[1,0]
	s_waitcnt vmcnt(7)
	v_pk_mul_f32 v[40:41], v[40:41], v[126:127] op_sel_hi:[1,0]
	v_pk_mul_f32 v[38:39], v[38:39], v[126:127] op_sel_hi:[1,0]
	s_waitcnt vmcnt(6)
	v_pk_mul_f32 v[36:37], v[36:37], v[128:129] op_sel_hi:[1,0]
	v_pk_mul_f32 v[34:35], v[34:35], v[128:129] op_sel_hi:[1,0]
	s_waitcnt vmcnt(5)
	v_pk_mul_f32 v[48:49], v[48:49], v[130:131] op_sel_hi:[1,0]
	v_pk_mul_f32 v[46:47], v[46:47], v[130:131] op_sel_hi:[1,0]
	s_waitcnt vmcnt(4)
	v_pk_mul_f32 v[44:45], v[44:45], v[132:133] op_sel_hi:[1,0]
	v_pk_mul_f32 v[42:43], v[42:43], v[132:133] op_sel_hi:[1,0]
	s_waitcnt vmcnt(3)
	v_pk_mul_f32 v[56:57], v[56:57], v[134:135] op_sel_hi:[1,0]
	v_pk_mul_f32 v[54:55], v[54:55], v[134:135] op_sel_hi:[1,0]
	s_waitcnt vmcnt(2)
	v_pk_mul_f32 v[52:53], v[52:53], v[136:137] op_sel_hi:[1,0]
	v_pk_mul_f32 v[50:51], v[50:51], v[136:137] op_sel_hi:[1,0]
	s_waitcnt vmcnt(1)
	v_pk_mul_f32 v[64:65], v[64:65], v[138:139] op_sel_hi:[1,0]
	v_pk_mul_f32 v[62:63], v[62:63], v[138:139] op_sel_hi:[1,0]
	s_waitcnt vmcnt(0)
	v_pk_mul_f32 v[60:61], v[60:61], v[140:141] op_sel_hi:[1,0]
	v_pk_mul_f32 v[58:59], v[58:59], v[140:141] op_sel_hi:[1,0]
	s_branch .LBB0_794
